# P8 GEMM main loop: the LDS-DMA loads of the 8- and 12-read phases issued from inside the MFMA block (after MFMA 4 and 8) instead of before the mid-phase barrier
# baseline (speedup 1.0000x reference)
; #define PG8_STAGE(bufoff, gbase, voff) do { _Pragma("unroll") for (int _i = 0; _i < 2; ++_i) \
;         __builtin_amdgcn_global_load_lds((const unsigned*)((const char*)(gbase) + (voff)[_i]), (PG8_LAS unsigned*)(lds + (bufoff) + ldsw + _i * 8192), 16, 0, 0); } while (0)
; #define PG8_LDA(dst, b, h) do { _Pragma("unroll") for (int m = 0; m < 4; ++m) _Pragma("unroll") for (int k = 0; k < 2; ++k) dst[m][k] = *(const PG8_LAS bf16x8*)(lds + PG8_SA(b, h) + aoff + m * 2048 + k * 1024); } while (0)
; #define PG8_LDB(dst, b, h) do { _Pragma("unroll") for (int n = 0; n < 2; ++n) _Pragma("unroll") for (int k = 0; k < 2; ++k) dst[n][k] = *(const PG8_LAS bf16x8*)(lds + PG8_SB(b, h) + boff + n * 2048 + k * 1024); } while (0)
; #define PG8_MMA(ai, bj, At, Bt) do { __builtin_amdgcn_s_setprio(1); _Pragma("unroll") for (int m = 0; m < 4; ++m) _Pragma("unroll") for (int n = 0; n < 2; ++n) _Pragma("unroll") for (int k = 0; k < 2; ++k) \
;         acc[ai][bj][m][n] = __builtin_amdgcn_mfma_f32_16x16x32_bf16(Bt[n][k], At[m][k], acc[ai][bj][m][n], 0, 0, 0); __builtin_amdgcn_s_setprio(0); } while (0)
; #define PG8_WAIT_L(n) asm volatile("s_waitcnt lgkmcnt(" #n ")" ::: "memory")
; #define PG8_BAR __builtin_amdgcn_s_barrier()
; #define PG8_SCHED __builtin_amdgcn_sched_barrier(0)
; template <class Epi>
; __device__ __forceinline__ void gemm_phase(PG8_LAS unsigned char* lds, const Gemm g, const StaticOrder& S, const Epi& E) {
;     ...
;             PG8_LDB(B0, 0, 0); PG8_SCHED; PG8_LDA(At, 0, 0); PG8_STAGE(PG8_SA(1, 1), a1 + hstep, voffA);
;             PG8_WAIT_L(8); PG8_BAR; PG8_WAIT_L(0); PG8_MMA(0, 0, At, B0); PG8_BAR; PG8_SCHED;
;             PG8_LDB(B1, 0, 1); PG8_STAGE(PG8_SB(0, 0), b2, voffB);
;             PG8_BAR; PG8_WAIT_L(0); PG8_MMA(0, 1, At, B1); PG8_BAR;
;             PG8_LDA(At, 0, 1); PG8_STAGE(PG8_SA(0, 0), a2, voffA);
;             PG8_BAR; PG8_WAIT_L(0); PG8_MMA(1, 0, At, B0); PG8_BAR; PG8_SCHED;
.LBB0_722:
	ds_read_b128 v[150:153], v159
	ds_read_b128 v[154:157], v159 offset:1024
	ds_read_b128 v[162:165], v159 offset:2048
	ds_read_b128 v[166:169], v159 offset:3072
	s_add_u32 s22, s20, 0xfff80080
	s_addc_u32 s23, s21, -1
	s_cmp_eq_u32 s50, 28
	s_cselect_b32 s25, s3, s23
	s_cselect_b32 s24, s5, s22
	s_cselect_b32 s23, s13, s49
	s_cselect_b32 s22, s15, s48
	v_lshl_add_u64 v[202:203], s[20:21], 0, v[142:143]
	s_add_i32 m0, s30, 0xc000
	ds_read_b128 v[170:173], v160
	ds_read_b128 v[174:177], v160 offset:1024
	ds_read_b128 v[178:181], v160 offset:2048
	ds_read_b128 v[182:185], v160 offset:3072
	ds_read_b128 v[186:189], v160 offset:4096
	ds_read_b128 v[190:193], v160 offset:5120
	ds_read_b128 v[194:197], v160 offset:6144
	ds_read_b128 v[198:201], v160 offset:7168
	s_waitcnt lgkmcnt(8)
	s_barrier
	s_waitcnt lgkmcnt(0)
	s_setprio 1
	s_waitcnt lgkmcnt(0)
	v_mfma_f32_16x16x32_bf16 v[126:129], v[150:153], v[170:173], v[126:129]
	v_mfma_f32_16x16x32_bf16 v[122:125], v[162:165], v[170:173], v[122:125]
	v_mfma_f32_16x16x32_bf16 v[110:113], v[150:153], v[178:181], v[110:113]
	v_mfma_f32_16x16x32_bf16 v[106:109], v[162:165], v[178:181], v[106:109]
	global_load_lds_dwordx4 v[202:203], off
	v_mfma_f32_16x16x32_bf16 v[94:97], v[150:153], v[186:189], v[94:97]
	v_mfma_f32_16x16x32_bf16 v[90:93], v[162:165], v[186:189], v[90:93]
	v_mfma_f32_16x16x32_bf16 v[78:81], v[150:153], v[194:197], v[78:81]
	v_mfma_f32_16x16x32_bf16 v[74:77], v[162:165], v[194:197], v[74:77]
	v_lshl_add_u64 v[202:203], s[20:21], 0, v[144:145]
	s_add_i32 m0, s30, 0xe000
	s_nop 0
	global_load_lds_dwordx4 v[202:203], off
	v_mfma_f32_16x16x32_bf16 v[126:129], v[154:157], v[174:177], v[126:129]
	v_mfma_f32_16x16x32_bf16 v[122:125], v[166:169], v[174:177], v[122:125]
	v_mfma_f32_16x16x32_bf16 v[110:113], v[154:157], v[182:185], v[110:113]
	v_mfma_f32_16x16x32_bf16 v[106:109], v[166:169], v[182:185], v[106:109]
	v_mfma_f32_16x16x32_bf16 v[94:97], v[154:157], v[190:193], v[94:97]
	v_mfma_f32_16x16x32_bf16 v[90:93], v[166:169], v[190:193], v[90:93]
	v_mfma_f32_16x16x32_bf16 v[78:81], v[154:157], v[198:201], v[78:81]
	v_mfma_f32_16x16x32_bf16 v[74:77], v[166:169], v[198:201], v[74:77]
	s_setprio 0
	s_barrier
	s_add_i32 s51, s43, s29
	v_lshl_add_u64 v[218:219], s[22:23], 0, v[134:135]
	s_mov_b32 m0, s51
	ds_read_b128 v[202:205], v161
	ds_read_b128 v[206:209], v161 offset:1024
	ds_read_b128 v[210:213], v161 offset:2048
	ds_read_b128 v[214:217], v161 offset:3072
	global_load_lds_dwordx4 v[218:219], off
	v_lshl_add_u64 v[220:221], s[22:23], 0, v[138:139]
	s_add_i32 m0, s51, 0x2000
	s_nop 0
	global_load_lds_dwordx4 v[220:221], off
	s_barrier
	s_waitcnt lgkmcnt(0)
	s_setprio 1
	s_waitcnt lgkmcnt(0)
	v_mfma_f32_16x16x32_bf16 v[118:121], v[202:205], v[170:173], v[118:121]
	v_mfma_f32_16x16x32_bf16 v[114:117], v[210:213], v[170:173], v[114:117]
	v_mfma_f32_16x16x32_bf16 v[102:105], v[202:205], v[178:181], v[102:105]
	v_mfma_f32_16x16x32_bf16 v[98:101], v[210:213], v[178:181], v[98:101]
	v_mfma_f32_16x16x32_bf16 v[86:89], v[202:205], v[186:189], v[86:89]
	v_mfma_f32_16x16x32_bf16 v[82:85], v[210:213], v[186:189], v[82:85]
	v_mfma_f32_16x16x32_bf16 v[70:73], v[202:205], v[194:197], v[70:73]
	v_mfma_f32_16x16x32_bf16 v[66:69], v[210:213], v[194:197], v[66:69]
	v_mfma_f32_16x16x32_bf16 v[118:121], v[206:209], v[174:177], v[118:121]
	v_mfma_f32_16x16x32_bf16 v[114:117], v[214:217], v[174:177], v[114:117]
	v_mfma_f32_16x16x32_bf16 v[102:105], v[206:209], v[182:185], v[102:105]
	v_mfma_f32_16x16x32_bf16 v[98:101], v[214:217], v[182:185], v[98:101]
	v_mfma_f32_16x16x32_bf16 v[86:89], v[206:209], v[190:193], v[86:89]
	v_mfma_f32_16x16x32_bf16 v[82:85], v[214:217], v[190:193], v[82:85]
	v_mfma_f32_16x16x32_bf16 v[70:73], v[206:209], v[198:201], v[70:73]
	v_mfma_f32_16x16x32_bf16 v[66:69], v[214:217], v[198:201], v[66:69]
	s_setprio 0
	s_mov_b32 m0, s30
	v_lshl_add_u64 v[222:223], s[24:25], 0, v[132:133]
	s_barrier
	ds_read_b128 v[170:173], v160 offset:16384
	ds_read_b128 v[174:177], v160 offset:17408
	ds_read_b128 v[178:181], v160 offset:18432
	ds_read_b128 v[182:185], v160 offset:19456
	ds_read_b128 v[186:189], v160 offset:20480
	ds_read_b128 v[190:193], v160 offset:21504
	ds_read_b128 v[194:197], v160 offset:22528
	ds_read_b128 v[198:201], v160 offset:23552
	s_barrier
	s_waitcnt lgkmcnt(0)
	s_setprio 1
	s_waitcnt lgkmcnt(0)
	v_mfma_f32_16x16x32_bf16 v[62:65], v[150:153], v[170:173], v[62:65]
	v_mfma_f32_16x16x32_bf16 v[58:61], v[162:165], v[170:173], v[58:61]
	v_mfma_f32_16x16x32_bf16 v[46:49], v[150:153], v[178:181], v[46:49]
	v_mfma_f32_16x16x32_bf16 v[42:45], v[162:165], v[178:181], v[42:45]
	global_load_lds_dwordx4 v[222:223], off
	v_mfma_f32_16x16x32_bf16 v[30:33], v[150:153], v[186:189], v[30:33]
	v_mfma_f32_16x16x32_bf16 v[26:29], v[162:165], v[186:189], v[26:29]
	v_mfma_f32_16x16x32_bf16 v[14:17], v[150:153], v[194:197], v[14:17]
	v_mfma_f32_16x16x32_bf16 v[10:13], v[162:165], v[194:197], v[10:13]
	v_lshl_add_u64 v[224:225], s[24:25], 0, v[136:137]
	s_mov_b32 m0, s31
	s_nop 0
	global_load_lds_dwordx4 v[224:225], off
	v_mfma_f32_16x16x32_bf16 v[62:65], v[154:157], v[174:177], v[62:65]
	v_mfma_f32_16x16x32_bf16 v[58:61], v[166:169], v[174:177], v[58:61]
	v_mfma_f32_16x16x32_bf16 v[46:49], v[154:157], v[182:185], v[46:49]
	v_mfma_f32_16x16x32_bf16 v[42:45], v[166:169], v[182:185], v[42:45]
	v_mfma_f32_16x16x32_bf16 v[30:33], v[154:157], v[190:193], v[30:33]
	v_mfma_f32_16x16x32_bf16 v[26:29], v[166:169], v[190:193], v[26:29]
	v_mfma_f32_16x16x32_bf16 v[14:17], v[154:157], v[198:201], v[14:17]
	v_mfma_f32_16x16x32_bf16 v[10:13], v[166:169], v[198:201], v[10:13]
	s_setprio 0
	s_barrier
; #define PG8_STAGE(bufoff, gbase, voff) do { _Pragma("unroll") for (int _i = 0; _i < 2; ++_i) \
;         __builtin_amdgcn_global_load_lds((const unsigned*)((const char*)(gbase) + (voff)[_i]), (PG8_LAS unsigned*)(lds + (bufoff) + ldsw + _i * 8192), 16, 0, 0); } while (0)
; #define PG8_LDA(dst, b, h) do { _Pragma("unroll") for (int m = 0; m < 4; ++m) _Pragma("unroll") for (int k = 0; k < 2; ++k) dst[m][k] = *(const PG8_LAS bf16x8*)(lds + PG8_SA(b, h) + aoff + m * 2048 + k * 1024); } while (0)
; #define PG8_LDB(dst, b, h) do { _Pragma("unroll") for (int n = 0; n < 2; ++n) _Pragma("unroll") for (int k = 0; k < 2; ++k) dst[n][k] = *(const PG8_LAS bf16x8*)(lds + PG8_SB(b, h) + boff + n * 2048 + k * 1024); } while (0)
; #define PG8_MMA(ai, bj, At, Bt) do { __builtin_amdgcn_s_setprio(1); _Pragma("unroll") for (int m = 0; m < 4; ++m) _Pragma("unroll") for (int n = 0; n < 2; ++n) _Pragma("unroll") for (int k = 0; k < 2; ++k) \
;         acc[ai][bj][m][n] = __builtin_amdgcn_mfma_f32_16x16x32_bf16(Bt[n][k], At[m][k], acc[ai][bj][m][n], 0, 0, 0); __builtin_amdgcn_s_setprio(0); } while (0)
; #define PG8_WAIT_V(n) asm volatile("s_waitcnt vmcnt(" #n ")" ::: "memory")
; #define PG8_WAIT_L(n) asm volatile("s_waitcnt lgkmcnt(" #n ")" ::: "memory")
; #define PG8_BAR __builtin_amdgcn_s_barrier()
; #define PG8_SCHED __builtin_amdgcn_sched_barrier(0)
; template <class Epi>
; __device__ __forceinline__ void gemm_phase(PG8_LAS unsigned char* lds, const Gemm g, const StaticOrder& S, const Epi& E) {
;     ...
;             PG8_STAGE(PG8_SB(0, 1), b2 + hstep, voffB);
;             PG8_WAIT_V(6); PG8_BAR; PG8_MMA(1, 1, At, B1); PG8_BAR;
;             PG8_LDB(B0, 1, 0); PG8_SCHED; PG8_LDA(At, 1, 0); PG8_STAGE(PG8_SA(0, 1), a2 + hstep, voffA);
;             PG8_WAIT_L(8); PG8_BAR; PG8_WAIT_L(0); PG8_MMA(0, 0, At, B0); PG8_BAR; PG8_SCHED;
;             PG8_LDB(B1, 1, 1); PG8_STAGE(PG8_SB(1, 0), b3, voffB);
;             PG8_BAR; PG8_WAIT_L(0); PG8_MMA(0, 1, At, B1); PG8_BAR;
	s_add_u32 s52, s22, 0x80000
	s_addc_u32 s53, s23, 0
	s_add_i32 s51, s44, s29
	v_lshl_add_u64 v[150:151], s[52:53], 0, v[134:135]
	s_mov_b32 m0, s51
	s_nop 0
	global_load_lds_dwordx4 v[150:151], off
	v_lshl_add_u64 v[150:151], s[52:53], 0, v[138:139]
	s_add_i32 m0, s51, 0x2000
	s_nop 0
	global_load_lds_dwordx4 v[150:151], off
	s_waitcnt vmcnt(6)
	s_barrier
	s_setprio 1
	v_mfma_f32_16x16x32_bf16 v[54:57], v[202:205], v[170:173], v[54:57]
	v_mfma_f32_16x16x32_bf16 v[50:53], v[210:213], v[170:173], v[50:53]
	v_mfma_f32_16x16x32_bf16 v[38:41], v[202:205], v[178:181], v[38:41]
	v_mfma_f32_16x16x32_bf16 v[34:37], v[210:213], v[178:181], v[34:37]
	v_mfma_f32_16x16x32_bf16 v[22:25], v[202:205], v[186:189], v[22:25]
	v_mfma_f32_16x16x32_bf16 v[18:21], v[210:213], v[186:189], v[18:21]
	v_mfma_f32_16x16x32_bf16 v[6:9], v[202:205], v[194:197], v[6:9]
	v_mfma_f32_16x16x32_bf16 v[2:5], v[210:213], v[194:197], v[2:5]
	v_mfma_f32_16x16x32_bf16 v[54:57], v[206:209], v[174:177], v[54:57]
	v_mfma_f32_16x16x32_bf16 v[50:53], v[214:217], v[174:177], v[50:53]
	v_mfma_f32_16x16x32_bf16 v[38:41], v[206:209], v[182:185], v[38:41]
	v_mfma_f32_16x16x32_bf16 v[34:37], v[214:217], v[182:185], v[34:37]
	v_mfma_f32_16x16x32_bf16 v[22:25], v[206:209], v[190:193], v[22:25]
	v_mfma_f32_16x16x32_bf16 v[18:21], v[214:217], v[190:193], v[18:21]
	v_mfma_f32_16x16x32_bf16 v[6:9], v[206:209], v[198:201], v[6:9]
	v_mfma_f32_16x16x32_bf16 v[2:5], v[214:217], v[198:201], v[2:5]
	s_setprio 0
	s_add_i32 s51, 0, 0x18000
	v_add_u32_e32 v140, s51, v131
	s_barrier
	ds_read_b128 v[150:153], v140
	ds_read_b128 v[154:157], v140 offset:1024
	ds_read_b128 v[162:165], v140 offset:2048
	ds_read_b128 v[166:169], v140 offset:3072
	s_add_u32 s24, s24, 0x80000
	s_addc_u32 s25, s25, 0
	s_mov_b32 m0, s33
	v_lshl_add_u64 v[202:203], s[24:25], 0, v[132:133]
	ds_read_b128 v[170:173], v160 offset:32768
	ds_read_b128 v[174:177], v160 offset:33792
	ds_read_b128 v[178:181], v160 offset:34816
	ds_read_b128 v[182:185], v160 offset:35840
	ds_read_b128 v[186:189], v160 offset:36864
	ds_read_b128 v[190:193], v160 offset:37888
	ds_read_b128 v[194:197], v160 offset:38912
	ds_read_b128 v[198:201], v160 offset:39936
	s_waitcnt lgkmcnt(8)
	s_barrier
	s_waitcnt lgkmcnt(0)
	s_setprio 1
	s_waitcnt lgkmcnt(0)
	v_mfma_f32_16x16x32_bf16 v[126:129], v[150:153], v[170:173], v[126:129]
	v_mfma_f32_16x16x32_bf16 v[122:125], v[162:165], v[170:173], v[122:125]
	v_mfma_f32_16x16x32_bf16 v[110:113], v[150:153], v[178:181], v[110:113]
	v_mfma_f32_16x16x32_bf16 v[106:109], v[162:165], v[178:181], v[106:109]
	global_load_lds_dwordx4 v[202:203], off
	v_mfma_f32_16x16x32_bf16 v[94:97], v[150:153], v[186:189], v[94:97]
	v_mfma_f32_16x16x32_bf16 v[90:93], v[162:165], v[186:189], v[90:93]
	v_mfma_f32_16x16x32_bf16 v[78:81], v[150:153], v[194:197], v[78:81]
	v_mfma_f32_16x16x32_bf16 v[74:77], v[162:165], v[194:197], v[74:77]
	v_lshl_add_u64 v[202:203], s[24:25], 0, v[136:137]
	s_mov_b32 m0, s34
	s_nop 0
	global_load_lds_dwordx4 v[202:203], off
	v_mfma_f32_16x16x32_bf16 v[126:129], v[154:157], v[174:177], v[126:129]
	v_mfma_f32_16x16x32_bf16 v[122:125], v[166:169], v[174:177], v[122:125]
	v_mfma_f32_16x16x32_bf16 v[110:113], v[154:157], v[182:185], v[110:113]
	v_mfma_f32_16x16x32_bf16 v[106:109], v[166:169], v[182:185], v[106:109]
	v_mfma_f32_16x16x32_bf16 v[94:97], v[154:157], v[190:193], v[94:97]
	v_mfma_f32_16x16x32_bf16 v[90:93], v[166:169], v[190:193], v[90:93]
	v_mfma_f32_16x16x32_bf16 v[78:81], v[154:157], v[198:201], v[78:81]
	v_mfma_f32_16x16x32_bf16 v[74:77], v[166:169], v[198:201], v[74:77]
	s_setprio 0
	s_barrier
	s_add_i32 s24, 0, 0x1c000
	s_add_i32 s25, s51, s29
	v_add_u32_e32 v140, s24, v131
	v_lshl_add_u64 v[218:219], v[218:219], 0, s[10:11]
	s_mov_b32 m0, s25
	ds_read_b128 v[202:205], v140
	ds_read_b128 v[206:209], v140 offset:1024
	ds_read_b128 v[210:213], v140 offset:2048
	ds_read_b128 v[214:217], v140 offset:3072
	global_load_lds_dwordx4 v[218:219], off
	v_lshl_add_u64 v[218:219], v[220:221], 0, s[10:11]
	s_add_i32 m0, s25, 0x2000
	s_nop 0
	global_load_lds_dwordx4 v[218:219], off
	s_barrier
	s_waitcnt lgkmcnt(0)
	s_setprio 1
	s_waitcnt lgkmcnt(0)
	v_mfma_f32_16x16x32_bf16 v[118:121], v[202:205], v[170:173], v[118:121]
	v_mfma_f32_16x16x32_bf16 v[114:117], v[210:213], v[170:173], v[114:117]
	v_mfma_f32_16x16x32_bf16 v[102:105], v[202:205], v[178:181], v[102:105]
	v_mfma_f32_16x16x32_bf16 v[98:101], v[210:213], v[178:181], v[98:101]
	v_mfma_f32_16x16x32_bf16 v[86:89], v[202:205], v[186:189], v[86:89]
	v_mfma_f32_16x16x32_bf16 v[82:85], v[210:213], v[186:189], v[82:85]
	v_mfma_f32_16x16x32_bf16 v[70:73], v[202:205], v[194:197], v[70:73]
	v_mfma_f32_16x16x32_bf16 v[66:69], v[210:213], v[194:197], v[66:69]
	v_mfma_f32_16x16x32_bf16 v[118:121], v[206:209], v[174:177], v[118:121]
	v_mfma_f32_16x16x32_bf16 v[114:117], v[214:217], v[174:177], v[114:117]
	v_mfma_f32_16x16x32_bf16 v[102:105], v[206:209], v[182:185], v[102:105]
	v_mfma_f32_16x16x32_bf16 v[98:101], v[214:217], v[182:185], v[98:101]
	v_mfma_f32_16x16x32_bf16 v[86:89], v[206:209], v[190:193], v[86:89]
	v_mfma_f32_16x16x32_bf16 v[82:85], v[214:217], v[190:193], v[82:85]
	v_mfma_f32_16x16x32_bf16 v[70:73], v[206:209], v[198:201], v[70:73]
	v_mfma_f32_16x16x32_bf16 v[66:69], v[214:217], v[198:201], v[66:69]
	s_setprio 0
	s_mov_b32 m0, s38
	v_lshl_add_u64 v[218:219], v[222:223], 0, s[10:11]
	s_barrier
; #define PG8_STAGE(bufoff, gbase, voff) do { _Pragma("unroll") for (int _i = 0; _i < 2; ++_i) \
;         __builtin_amdgcn_global_load_lds((const unsigned*)((const char*)(gbase) + (voff)[_i]), (PG8_LAS unsigned*)(lds + (bufoff) + ldsw + _i * 8192), 16, 0, 0); } while (0)
; #define PG8_LDA(dst, b, h) do { _Pragma("unroll") for (int m = 0; m < 4; ++m) _Pragma("unroll") for (int k = 0; k < 2; ++k) dst[m][k] = *(const PG8_LAS bf16x8*)(lds + PG8_SA(b, h) + aoff + m * 2048 + k * 1024); } while (0)
; #define PG8_MMA(ai, bj, At, Bt) do { __builtin_amdgcn_s_setprio(1); _Pragma("unroll") for (int m = 0; m < 4; ++m) _Pragma("unroll") for (int n = 0; n < 2; ++n) _Pragma("unroll") for (int k = 0; k < 2; ++k) \
;         acc[ai][bj][m][n] = __builtin_amdgcn_mfma_f32_16x16x32_bf16(Bt[n][k], At[m][k], acc[ai][bj][m][n], 0, 0, 0); __builtin_amdgcn_s_setprio(0); } while (0)
; #define PG8_WAIT_V(n) asm volatile("s_waitcnt vmcnt(" #n ")" ::: "memory")
; #define PG8_WAIT_L(n) asm volatile("s_waitcnt lgkmcnt(" #n ")" ::: "memory")
; #define PG8_BAR __builtin_amdgcn_s_barrier()
; #define PG8_SCHED __builtin_amdgcn_sched_barrier(0)
; template <class Epi>
; __device__ __forceinline__ void gemm_phase(PG8_LAS unsigned char* lds, const Gemm g, const StaticOrder& S, const Epi& E) {
;     ...
;             PG8_LDA(At, 1, 1); PG8_STAGE(PG8_SA(1, 0), a3, voffA);
;             PG8_BAR; PG8_WAIT_L(0); PG8_MMA(1, 0, At, B0); PG8_BAR; PG8_SCHED;
;             PG8_STAGE(PG8_SB(1, 1), b3 + hstep, voffB);
;             PG8_WAIT_V(6); PG8_BAR; PG8_MMA(1, 1, At, B1); PG8_BAR;
;         }
;         E(acc, cur, wr, wc, fr, fq);
	ds_read_b128 v[170:173], v160 offset:49152
	ds_read_b128 v[174:177], v160 offset:50176
	ds_read_b128 v[178:181], v160 offset:51200
	ds_read_b128 v[182:185], v160 offset:52224
	ds_read_b128 v[186:189], v160 offset:53248
	ds_read_b128 v[190:193], v160 offset:54272
	ds_read_b128 v[194:197], v160 offset:55296
	ds_read_b128 v[198:201], v160 offset:56320
	s_barrier
	s_waitcnt lgkmcnt(0)
	s_setprio 1
	s_waitcnt lgkmcnt(0)
	v_mfma_f32_16x16x32_bf16 v[62:65], v[150:153], v[170:173], v[62:65]
	v_mfma_f32_16x16x32_bf16 v[58:61], v[162:165], v[170:173], v[58:61]
	v_mfma_f32_16x16x32_bf16 v[46:49], v[150:153], v[178:181], v[46:49]
	v_mfma_f32_16x16x32_bf16 v[42:45], v[162:165], v[178:181], v[42:45]
	global_load_lds_dwordx4 v[218:219], off
	v_mfma_f32_16x16x32_bf16 v[30:33], v[150:153], v[186:189], v[30:33]
	v_mfma_f32_16x16x32_bf16 v[26:29], v[162:165], v[186:189], v[26:29]
	v_mfma_f32_16x16x32_bf16 v[14:17], v[150:153], v[194:197], v[14:17]
	v_mfma_f32_16x16x32_bf16 v[10:13], v[162:165], v[194:197], v[10:13]
	v_lshl_add_u64 v[218:219], v[224:225], 0, s[10:11]
	s_mov_b32 m0, s39
	s_nop 0
	global_load_lds_dwordx4 v[218:219], off
	v_mfma_f32_16x16x32_bf16 v[62:65], v[154:157], v[174:177], v[62:65]
	v_mfma_f32_16x16x32_bf16 v[58:61], v[166:169], v[174:177], v[58:61]
	v_mfma_f32_16x16x32_bf16 v[46:49], v[154:157], v[182:185], v[46:49]
	v_mfma_f32_16x16x32_bf16 v[42:45], v[166:169], v[182:185], v[42:45]
	v_mfma_f32_16x16x32_bf16 v[30:33], v[154:157], v[190:193], v[30:33]
	v_mfma_f32_16x16x32_bf16 v[26:29], v[166:169], v[190:193], v[26:29]
	v_mfma_f32_16x16x32_bf16 v[14:17], v[154:157], v[198:201], v[14:17]
	v_mfma_f32_16x16x32_bf16 v[10:13], v[166:169], v[198:201], v[10:13]
	s_setprio 0
	s_barrier
	s_add_u32 s22, s22, 0x80080
	s_addc_u32 s23, s23, 0
	s_add_i32 s24, s24, s29
	v_lshl_add_u64 v[150:151], s[22:23], 0, v[134:135]
	s_mov_b32 m0, s24
	s_nop 0
	global_load_lds_dwordx4 v[150:151], off
	v_lshl_add_u64 v[150:151], s[22:23], 0, v[138:139]
	s_add_i32 m0, s24, 0x2000
	s_nop 0
	global_load_lds_dwordx4 v[150:151], off
	s_waitcnt vmcnt(6)
	s_barrier
	s_setprio 1
	v_mfma_f32_16x16x32_bf16 v[54:57], v[202:205], v[170:173], v[54:57]
	v_mfma_f32_16x16x32_bf16 v[50:53], v[210:213], v[170:173], v[50:53]
	v_mfma_f32_16x16x32_bf16 v[38:41], v[202:205], v[178:181], v[38:41]
	v_mfma_f32_16x16x32_bf16 v[34:37], v[210:213], v[178:181], v[34:37]
	v_mfma_f32_16x16x32_bf16 v[22:25], v[202:205], v[186:189], v[22:25]
	v_mfma_f32_16x16x32_bf16 v[18:21], v[210:213], v[186:189], v[18:21]
	v_mfma_f32_16x16x32_bf16 v[6:9], v[202:205], v[194:197], v[6:9]
	v_mfma_f32_16x16x32_bf16 v[2:5], v[210:213], v[194:197], v[2:5]
	v_mfma_f32_16x16x32_bf16 v[54:57], v[206:209], v[174:177], v[54:57]
	v_mfma_f32_16x16x32_bf16 v[50:53], v[214:217], v[174:177], v[50:53]
	v_mfma_f32_16x16x32_bf16 v[38:41], v[206:209], v[182:185], v[38:41]
	v_mfma_f32_16x16x32_bf16 v[34:37], v[214:217], v[182:185], v[34:37]
	v_mfma_f32_16x16x32_bf16 v[22:25], v[206:209], v[190:193], v[22:25]
	v_mfma_f32_16x16x32_bf16 v[18:21], v[214:217], v[190:193], v[18:21]
	v_mfma_f32_16x16x32_bf16 v[6:9], v[206:209], v[198:201], v[6:9]
	v_mfma_f32_16x16x32_bf16 v[2:5], v[214:217], v[198:201], v[2:5]
	s_setprio 0
	s_add_i32 s50, s50, 2
	s_add_u32 s20, s20, 0x100
	s_addc_u32 s21, s21, 0
	s_add_u32 s48, s48, 0x100
	s_addc_u32 s49, s49, 0
	s_cmp_gt_u32 s50, 29
	s_barrier
	s_cbranch_scc0 .LBB0_722
	v_lshl_add_u32 v152, s2, 8, v1
	s_lshl_b32 s13, s4, 8
	v_or_b32_e32 v150, s13, v158
	v_mad_i64_i32 v[154:155], s[2:3], v152, s45, 0
	v_cmp_lt_i32_e64 s[2:3], s46, v150
	s_and_saveexec_b64 s[20:21], s[2:3]
	s_xor_b64 s[20:21], exec, s[20:21]
	s_cbranch_execz .LBB0_726
	s_cmpk_gt_u32 s13, 0x317f
	s_cbranch_scc1 .LBB0_726
	v_lshl_add_u64 v[156:157], s[8:9], 0, v[154:155]
	v_mov_b32_e32 v151, v141
	v_lshl_add_u64 v[156:157], v[150:151], 1, v[156:157]
	v_add_co_u32_e32 v156, vcc, 0xffffa000, v156
	v_cvt_pk_bf16_f32 v162, v126, v127
	v_cvt_pk_bf16_f32 v163, v128, v129
	v_cvt_pk_bf16_f32 v164, v122, v123
	v_cvt_pk_bf16_f32 v165, v124, v125
	s_nop 1
	v_addc_co_u32_e32 v157, vcc, -1, v157, vcc
	global_store_dwordx4 v[156:157], v[162:165], off
